# P0 panel arrivals combined per workgroup (wave 0 adds 8 after a barrier) instead of one atomic per wave and panel
# baseline (speedup 1.0000x reference)
; __device__ __forceinline__ int tid_of(int wave) { return wave * 64 + lane_id(); }
; __device__ __forceinline__ unsigned xb_ld(unsigned* p)              { return __hip_atomic_load(p, __ATOMIC_RELAXED, __HIP_MEMORY_SCOPE_AGENT); }
; __device__ __forceinline__ unsigned xb_add(unsigned* p, unsigned v) { return __hip_atomic_fetch_add(p, v, __ATOMIC_RELAXED, __HIP_MEMORY_SCOPE_AGENT); }
; #define XB_SPIN(cond, bar) do { unsigned _sp = 0; while (cond) { __builtin_amdgcn_s_sleep(1); \
;     if ((++_sp & 255u) == 0u) { if (xb_ld(&(bar)[XB_TMO])) break; if (_sp > XB_SPIN_CAP) { atomicAdd(&(bar)[XB_TMO], 1u); break; } } } } while (0)
; __device__ __forceinline__ void xcd_barrier(const XcdBarrier& b) {
;     asm volatile("s_waitcnt vmcnt(0)" ::: "memory");
;     __syncthreads();
;     if (tid_of(b.w) == 0) {
;         unsigned* bar = b.bar;
;         __builtin_amdgcn_s_waitcnt(0);
;         unsigned nloc = b.st[0], nx = b.st[1];
;         if (nloc == 0u) { xcd_barrier_complete(bar, b.x, nloc, nx); b.st[0] = nloc; b.st[1] = nx; }
;         const unsigned old = xb_add(&bar[XB_XSUB(b.x)], 1u);
;         const unsigned gen = old / nloc;
;         if (old + 1u == (gen + 1u) * nloc) {
;             __builtin_amdgcn_fence(__ATOMIC_RELEASE, "agent");
;             asm volatile("s_waitcnt vmcnt(0)" ::: "memory");
;             const unsigned og = xb_add(&bar[XB_TOP], 1u);
;             const unsigned tg = og / nx;
;             if (og + 1u == (tg + 1u) * nx) xb_add(&bar[XB_TOPGEN], 1u);
;             else XB_SPIN(xb_ld(&bar[XB_TOPGEN]) == tg, bar);
;             __builtin_amdgcn_fence(__ATOMIC_ACQUIRE, "agent");
;             xb_add(&bar[XB_XGEN(b.x)], 1u);
;             asm volatile("s_waitcnt vmcnt(0)" ::: "memory");
;         } else {
;             XB_SPIN(xb_ld(&bar[XB_XGEN(b.x)]) == gen, bar);
;             __builtin_amdgcn_fence(__ATOMIC_ACQUIRE, "agent");
;             asm volatile("s_waitcnt vmcnt(0)" ::: "memory");
;         }
;     }
;     __syncthreads();
; }
.LBB0_63:
	s_waitcnt vmcnt(0)
	s_barrier
	s_cmp_gt_u32 s67, 63
	s_cbranch_scc1 .Lp0_arr_done
	s_lshr_b32 s98, s96, 8
	s_lshl_b32 s98, s98, 6
	s_add_i32 s98, s98, 0x3800
	v_mov_b32_e32 v236, s98
	v_mov_b32_e32 v237, 8
	s_mov_b64 s[100:101], exec
	s_mov_b64 exec, 1
	global_atomic_add v236, v237, s[68:69]
	s_mov_b64 exec, s[100:101]
	s_add_i32 s98, s98, 0x200
	v_mov_b32_e32 v236, s98
	v_mov_b32_e32 v237, 8
	s_mov_b64 s[100:101], exec
	s_mov_b64 exec, 1
	global_atomic_add v236, v237, s[68:69]
	s_mov_b64 exec, s[100:101]
	s_add_i32 s98, s98, 0x200
	v_mov_b32_e32 v236, s98
	v_mov_b32_e32 v237, 8
	s_mov_b64 s[100:101], exec
	s_mov_b64 exec, 1
	global_atomic_add v236, v237, s[68:69]
	s_mov_b64 exec, s[100:101]
	s_add_i32 s98, s98, 0x200
	v_mov_b32_e32 v236, s98
	v_mov_b32_e32 v237, 8
	s_mov_b64 s[100:101], exec
	s_mov_b64 exec, 1
	global_atomic_add v236, v237, s[68:69]
	s_mov_b64 exec, s[100:101]
.Lp0_arr_done:
	v_readlane_b32 s8, v248, 0
	v_readlane_b32 s9, v248, 1
	s_cmp_gt_i32 s9, 1
	s_cselect_b64 s[0:1], -1, 0
	s_and_b64 s[4:5], s[6:7], s[0:1]
	s_andn2_b64 vcc, exec, s[4:5]
	v_readlane_b32 s10, v248, 2
	v_readlane_b32 s11, v248, 3
	s_cmpk_eq_i32 s88, 0x100
	s_cbranch_scc1 .LBB0_117
	s_cbranch_vccnz .LBB0_117
	s_waitcnt vmcnt(0)
	s_barrier
	s_mov_b64 s[4:5], exec
	v_readlane_b32 s6, v248, 4
	v_readlane_b32 s7, v248, 5
	s_and_b64 s[6:7], s[4:5], s[6:7]
	s_mov_b64 exec, s[6:7]
	s_cbranch_execz .LBB0_116
	s_add_i32 s6, 0, 0x24fe0
	v_mov_b32_e32 v0, s6
	s_waitcnt vmcnt(0) expcnt(0) lgkmcnt(0)
	ds_read_b32 v2, v0
	s_add_i32 s6, 0, 0x24fe4
	v_mov_b32_e32 v0, s6
	ds_read_b32 v0, v0
	s_waitcnt lgkmcnt(1)
	v_cmp_ne_u32_e32 vcc, 0, v2
	s_cbranch_vccnz .LBB0_80
	s_add_u32 s6, s68, 0x1000
	s_addc_u32 s7, s69, 0
	s_add_u32 s8, s68, 0x1100
	s_addc_u32 s9, s69, 0
	s_add_u32 s10, s68, 0x1200
	s_addc_u32 s11, s69, 0
	s_mul_i32 s20, s89, s90
	s_add_u32 s12, s68, 0x1300
	s_mul_i32 s20, s20, s88
	s_addc_u32 s13, s69, 0
	s_mov_b32 s21, 1
	v_mov_b32_e32 v16, 0
	s_branch .LBB0_68
